# v36 + compress bias reduction moved from phase 0 to the NSA-in idle window (workgroups 254/255), 128 extra rmsnorm rows given to the waves without a weight item
# baseline (speedup 1.0000x reference)
.LBB0_162:
	s_add_i32 s4, s10, s43
	s_cmpk_lt_i32 s4, 0x4000
	s_cbranch_scc1 .LBB0_163
	s_addk_i32 s4, -1920
	s_cmpk_lt_i32 s4, 0x4000
	s_cbranch_scc1 .LBB0_165
	s_cmpk_gt_i32 s4, 0x407f
	s_cbranch_scc1 .LBB0_165

.LBB0_238:
	v_writelane_b32 v254, s12, 12
	s_nop 1
	v_writelane_b32 v254, s13, 13
	s_or_b64 exec, exec, s[4:5]
	s_not_b32 s2, s72
	s_add_i32 s2, s38, s2
	s_branch .LBB0_244
.Lbias_entry:
	v_lshlrev_b32_e32 v2, 1, v0
	s_barrier
	s_load_dwordx2 s[4:5], s[0:1], 0x60
	s_load_dwordx2 s[6:7], s[0:1], 0x70
	v_and_b32_e32 v2, 0x380, v2
	v_lshl_add_u32 v2, s38, 6, v2
	v_or_b32_e32 v2, v2, v20
	s_lshl_b32 s3, s72, 6
	v_subrev_u32_e32 v2, s3, v2
	v_add_u32_e32 v4, 0x2000, v1
	v_subrev_u32_e32 v2, 64, v2
	v_or_b32_e32 v5, 0xfffffe00, v0
	s_mov_b64 s[8:9], 0
	v_mov_b32_e32 v3, 0
	s_movk_i32 s3, 0x5ff

.LBB0_243:
	s_or_b64 exec, exec, s[4:5]
	s_barrier
	s_branch .Lbias_ret

.LBB0_640:
	s_waitcnt vmcnt(0)
	s_barrier
	s_cmpk_lt_u32 s86, 203
	s_cbranch_scc1 .Lcv1_skip
	v_writelane_b32 v200, s2, 0
	v_writelane_b32 v200, s3, 1
	v_writelane_b32 v200, s4, 2
	v_writelane_b32 v200, s5, 3
	v_writelane_b32 v200, s6, 4
	v_writelane_b32 v200, s7, 5
	v_writelane_b32 v200, s8, 6
	v_writelane_b32 v200, s9, 7
	v_writelane_b32 v200, s10, 8
	v_writelane_b32 v200, s11, 9
	v_writelane_b32 v200, s12, 10
	v_writelane_b32 v200, s13, 11
	v_writelane_b32 v200, s14, 12
	v_writelane_b32 v200, s15, 13
	v_writelane_b32 v200, s16, 14
	v_writelane_b32 v200, s17, 15
	v_writelane_b32 v200, s18, 16
	v_writelane_b32 v200, s19, 17
	v_writelane_b32 v200, s20, 18
	v_writelane_b32 v200, s21, 19
	v_writelane_b32 v200, s22, 20
	v_writelane_b32 v200, s23, 21
	v_writelane_b32 v200, s24, 22
	v_writelane_b32 v200, s25, 23
	v_writelane_b32 v200, s26, 24
	v_writelane_b32 v200, s27, 25
	v_writelane_b32 v200, s28, 26
	v_writelane_b32 v200, s29, 27
	v_writelane_b32 v200, s30, 28
	v_writelane_b32 v200, s31, 29
	v_writelane_b32 v200, s32, 30
	v_writelane_b32 v200, s33, 31
	v_writelane_b32 v200, s34, 32
	v_writelane_b32 v200, s35, 33
	v_writelane_b32 v200, s36, 34
	v_writelane_b32 v200, s37, 35
	v_writelane_b32 v200, s38, 36
	v_writelane_b32 v200, s39, 37
	v_writelane_b32 v200, s40, 38
	v_writelane_b32 v200, s41, 39
	v_writelane_b32 v200, s42, 40
	v_writelane_b32 v200, s43, 41
	v_writelane_b32 v200, s44, 42
	v_writelane_b32 v200, s45, 43
	v_writelane_b32 v200, s46, 44
	v_writelane_b32 v200, s47, 45
	v_writelane_b32 v200, s48, 46
	v_writelane_b32 v200, s49, 47
	v_writelane_b32 v200, s50, 48
	v_writelane_b32 v200, s51, 49
	v_writelane_b32 v200, s52, 50
	v_writelane_b32 v200, s53, 51
	v_writelane_b32 v200, s54, 52
	v_writelane_b32 v200, s55, 53
	v_writelane_b32 v200, s56, 54
	v_writelane_b32 v200, s57, 55
	v_writelane_b32 v200, s58, 56
	v_writelane_b32 v200, s59, 57
	v_writelane_b32 v200, s60, 58
	v_writelane_b32 v200, s61, 59
	v_writelane_b32 v200, s62, 60
	v_writelane_b32 v200, s63, 61
	v_writelane_b32 v200, s64, 62
	v_writelane_b32 v200, s65, 63
	v_writelane_b32 v201, s66, 0
	v_writelane_b32 v201, s67, 1
	v_writelane_b32 v201, s68, 2
	v_writelane_b32 v201, s69, 3
	v_writelane_b32 v201, s70, 4
	v_writelane_b32 v201, s71, 5
	v_writelane_b32 v201, s72, 6
	v_writelane_b32 v201, s73, 7
	v_writelane_b32 v201, s74, 8
	v_writelane_b32 v201, s75, 9
	v_writelane_b32 v201, s76, 10
	v_writelane_b32 v201, s77, 11
	v_writelane_b32 v201, s78, 12
	v_writelane_b32 v201, s79, 13
	v_writelane_b32 v201, s80, 14
	v_writelane_b32 v201, s81, 15
	v_writelane_b32 v201, s82, 16
	v_writelane_b32 v201, s83, 17
	v_writelane_b32 v201, s84, 18
	v_writelane_b32 v201, s85, 19
	v_writelane_b32 v201, s86, 20
	v_writelane_b32 v201, s87, 21
	v_writelane_b32 v201, s88, 22
	v_writelane_b32 v201, s89, 23
	v_writelane_b32 v201, s90, 24
	v_writelane_b32 v201, s91, 25
	v_writelane_b32 v201, s92, 26
	v_writelane_b32 v201, s93, 27
	v_writelane_b32 v201, s94, 28
	v_writelane_b32 v201, s95, 29
	v_writelane_b32 v201, s96, 30
	v_writelane_b32 v201, s97, 31
	v_writelane_b32 v201, s98, 32
	v_writelane_b32 v201, s99, 33
	s_cmpk_lt_u32 s86, 254
	s_cbranch_scc1 .Lcv1_items
	v_mbcnt_lo_u32_b32 v0, -1, 0
	v_mbcnt_hi_u32_b32 v0, -1, v0
	v_lshl_add_u32 v0, s87, 6, v0
	v_lshlrev_b32_e32 v1, 2, v0
	v_and_b32_e32 v20, 63, v0
	s_mov_b32 s72, s86
	s_mov_b64 s[78:79], s[90:91]
	s_not_b32 s2, s72
	s_add_i32 s2, s38, s2
	s_branch .Lbias_entry
.Lcv1_items:
	v_mbcnt_lo_u32_b32 v0, -1, 0
	v_mbcnt_hi_u32_b32 v0, -1, v0
	v_and_b32_e32 v21, 31, v0
	v_bfe_u32 v31, v0, 5, 1
	v_lshlrev_b32_e32 v2, 2, v21
	v_mul_u32_u24_e32 v3, 0x84, v31
	v_bfe_u32 v29, v0, 3, 3
	s_lshl_b32 s2, s87, 14
	s_add_i32 s3, s2, 0
	v_add3_u32 v28, s3, v2, v3
	v_lshlrev_b32_e32 v2, 3, v0
	v_and_b32_e32 v2, 56, v2
	v_mul_u32_u24_e32 v4, 0x84, v2
	v_lshlrev_b32_e32 v5, 2, v29
	s_mov_b32 s7, 0
	v_mov_b32_e32 v3, 0
	v_add3_u32 v30, s3, v4, v5
	v_lshlrev_b32_e32 v18, 1, v2
	s_sub_i32 s2, s86, 203
	s_lshl_b32 s2, s2, 3
	s_add_i32 s2, s2, s87
	s_addk_i32 s2, 0x1000
	s_movk_i32 s43, 0x198
	s_movk_i32 s100, 0x1fff
	s_mov_b32 s101, 1
	s_branch .Lcv_loop_entry
.Lbias_ret:
.Lcv1_ret:
	v_readlane_b32 s2, v200, 0
	v_readlane_b32 s3, v200, 1
	v_readlane_b32 s4, v200, 2
	v_readlane_b32 s5, v200, 3
	v_readlane_b32 s6, v200, 4
	v_readlane_b32 s7, v200, 5
	v_readlane_b32 s8, v200, 6
	v_readlane_b32 s9, v200, 7
	v_readlane_b32 s10, v200, 8
	v_readlane_b32 s11, v200, 9
	v_readlane_b32 s12, v200, 10
	v_readlane_b32 s13, v200, 11
	v_readlane_b32 s14, v200, 12
	v_readlane_b32 s15, v200, 13
	v_readlane_b32 s16, v200, 14
	v_readlane_b32 s17, v200, 15
	v_readlane_b32 s18, v200, 16
	v_readlane_b32 s19, v200, 17
	v_readlane_b32 s20, v200, 18
	v_readlane_b32 s21, v200, 19
	v_readlane_b32 s22, v200, 20
	v_readlane_b32 s23, v200, 21
	v_readlane_b32 s24, v200, 22
	v_readlane_b32 s25, v200, 23
	v_readlane_b32 s26, v200, 24
	v_readlane_b32 s27, v200, 25
	v_readlane_b32 s28, v200, 26
	v_readlane_b32 s29, v200, 27
	v_readlane_b32 s30, v200, 28
	v_readlane_b32 s31, v200, 29
	v_readlane_b32 s32, v200, 30
	v_readlane_b32 s33, v200, 31
	v_readlane_b32 s34, v200, 32
	v_readlane_b32 s35, v200, 33
	v_readlane_b32 s36, v200, 34
	v_readlane_b32 s37, v200, 35
	v_readlane_b32 s38, v200, 36
	v_readlane_b32 s39, v200, 37
	v_readlane_b32 s40, v200, 38
	v_readlane_b32 s41, v200, 39
	v_readlane_b32 s42, v200, 40
	v_readlane_b32 s43, v200, 41
	v_readlane_b32 s44, v200, 42
	v_readlane_b32 s45, v200, 43
	v_readlane_b32 s46, v200, 44
	v_readlane_b32 s47, v200, 45
	v_readlane_b32 s48, v200, 46
	v_readlane_b32 s49, v200, 47
	v_readlane_b32 s50, v200, 48
	v_readlane_b32 s51, v200, 49
	v_readlane_b32 s52, v200, 50
	v_readlane_b32 s53, v200, 51
	v_readlane_b32 s54, v200, 52
	v_readlane_b32 s55, v200, 53
	v_readlane_b32 s56, v200, 54
	v_readlane_b32 s57, v200, 55
	v_readlane_b32 s58, v200, 56
	v_readlane_b32 s59, v200, 57
	v_readlane_b32 s60, v200, 58
	v_readlane_b32 s61, v200, 59
	v_readlane_b32 s62, v200, 60
	v_readlane_b32 s63, v200, 61
	v_readlane_b32 s64, v200, 62
	v_readlane_b32 s65, v200, 63
	v_readlane_b32 s66, v201, 0
	v_readlane_b32 s67, v201, 1
	v_readlane_b32 s68, v201, 2
	v_readlane_b32 s69, v201, 3
	v_readlane_b32 s70, v201, 4
	v_readlane_b32 s71, v201, 5
	v_readlane_b32 s72, v201, 6
	v_readlane_b32 s73, v201, 7
	v_readlane_b32 s74, v201, 8
	v_readlane_b32 s75, v201, 9
	v_readlane_b32 s76, v201, 10
	v_readlane_b32 s77, v201, 11
	v_readlane_b32 s78, v201, 12
	v_readlane_b32 s79, v201, 13
	v_readlane_b32 s80, v201, 14
	v_readlane_b32 s81, v201, 15
	v_readlane_b32 s82, v201, 16
	v_readlane_b32 s83, v201, 17
	v_readlane_b32 s84, v201, 18
	v_readlane_b32 s85, v201, 19
	v_readlane_b32 s86, v201, 20
	v_readlane_b32 s87, v201, 21
	v_readlane_b32 s88, v201, 22
	v_readlane_b32 s89, v201, 23
	v_readlane_b32 s90, v201, 24
	v_readlane_b32 s91, v201, 25
	v_readlane_b32 s92, v201, 26
	v_readlane_b32 s93, v201, 27
	v_readlane_b32 s94, v201, 28
	v_readlane_b32 s95, v201, 29
	v_readlane_b32 s96, v201, 30
	v_readlane_b32 s97, v201, 31
	v_readlane_b32 s98, v201, 32
	v_readlane_b32 s99, v201, 33
